# mod phase: the 34 serialized load/silu/store steps staging silu(cond) batched into one load group
# baseline (speedup 1.0000x reference)
.LBB0_290:
	s_barrier
	s_and_saveexec_b64 s[4:5], s[8:9]
	s_cbranch_execz .LBB0_293
	v_mov_b64_e32 v[108:109], v[10:11]
	s_mov_b64 s[14:15], 0x1000
	global_load_dword v112, v[108:109], off
	global_load_dword v113, v[108:109], off offset:2048
	v_lshl_add_u64 v[108:109], v[108:109], 0, s[14:15]
	global_load_dword v114, v[108:109], off
	global_load_dword v115, v[108:109], off offset:2048
	v_lshl_add_u64 v[108:109], v[108:109], 0, s[14:15]
	global_load_dword v116, v[108:109], off
	global_load_dword v117, v[108:109], off offset:2048
	v_lshl_add_u64 v[108:109], v[108:109], 0, s[14:15]
	global_load_dword v118, v[108:109], off
	global_load_dword v119, v[108:109], off offset:2048
	v_lshl_add_u64 v[108:109], v[108:109], 0, s[14:15]
	global_load_dword v120, v[108:109], off
	global_load_dword v121, v[108:109], off offset:2048
	v_lshl_add_u64 v[108:109], v[108:109], 0, s[14:15]
	global_load_dword v122, v[108:109], off
	global_load_dword v123, v[108:109], off offset:2048
	v_lshl_add_u64 v[108:109], v[108:109], 0, s[14:15]
	global_load_dword v124, v[108:109], off
	global_load_dword v125, v[108:109], off offset:2048
	v_lshl_add_u64 v[108:109], v[108:109], 0, s[14:15]
	global_load_dword v126, v[108:109], off
	global_load_dword v127, v[108:109], off offset:2048
	v_lshl_add_u64 v[108:109], v[108:109], 0, s[14:15]
	global_load_dword v128, v[108:109], off
	global_load_dword v129, v[108:109], off offset:2048
	v_lshl_add_u64 v[108:109], v[108:109], 0, s[14:15]
	global_load_dword v130, v[108:109], off
	global_load_dword v131, v[108:109], off offset:2048
	v_lshl_add_u64 v[108:109], v[108:109], 0, s[14:15]
	global_load_dword v132, v[108:109], off
	global_load_dword v133, v[108:109], off offset:2048
	v_lshl_add_u64 v[108:109], v[108:109], 0, s[14:15]
	global_load_dword v134, v[108:109], off
	global_load_dword v135, v[108:109], off offset:2048
	v_lshl_add_u64 v[108:109], v[108:109], 0, s[14:15]
	global_load_dword v136, v[108:109], off
	global_load_dword v137, v[108:109], off offset:2048
	v_lshl_add_u64 v[108:109], v[108:109], 0, s[14:15]
	global_load_dword v164, v[108:109], off
	global_load_dword v165, v[108:109], off offset:2048
	v_lshl_add_u64 v[108:109], v[108:109], 0, s[14:15]
	global_load_dword v166, v[108:109], off
	global_load_dword v167, v[108:109], off offset:2048
	v_lshl_add_u64 v[108:109], v[108:109], 0, s[14:15]
	global_load_dword v168, v[108:109], off
	global_load_dword v169, v[108:109], off offset:2048
	v_and_b32_e32 v110, 0x3ff, v4
	v_lshlrev_b32_e32 v110, 2, v110
	v_mov_b32_e32 v111, v2
	v_lshl_add_u64 v[110:111], s[12:13], 0, v[110:111]
	global_load_dword v170, v[110:111], off
	global_load_dword v171, v[110:111], off offset:2048
	s_waitcnt vmcnt(0)
	v_mul_f32_e32 v172, 0xbfb8aa3b, v112
	v_mul_f32_e32 v173, 0xbfb8aa3b, v113
	v_mul_f32_e32 v174, 0xbfb8aa3b, v114
	v_mul_f32_e32 v175, 0xbfb8aa3b, v115
	v_mul_f32_e32 v176, 0xbfb8aa3b, v116
	v_mul_f32_e32 v177, 0xbfb8aa3b, v117
	v_mul_f32_e32 v178, 0xbfb8aa3b, v118
	v_mul_f32_e32 v179, 0xbfb8aa3b, v119
	v_mul_f32_e32 v180, 0xbfb8aa3b, v120
	v_mul_f32_e32 v181, 0xbfb8aa3b, v121
	v_mul_f32_e32 v182, 0xbfb8aa3b, v122
	v_mul_f32_e32 v183, 0xbfb8aa3b, v123
	v_mul_f32_e32 v184, 0xbfb8aa3b, v124
	v_mul_f32_e32 v185, 0xbfb8aa3b, v125
	v_mul_f32_e32 v186, 0xbfb8aa3b, v126
	v_mul_f32_e32 v187, 0xbfb8aa3b, v127
	v_mul_f32_e32 v188, 0xbfb8aa3b, v128
	v_mul_f32_e32 v189, 0xbfb8aa3b, v129
	v_mul_f32_e32 v190, 0xbfb8aa3b, v130
	v_mul_f32_e32 v191, 0xbfb8aa3b, v131
	v_mul_f32_e32 v192, 0xbfb8aa3b, v132
	v_mul_f32_e32 v193, 0xbfb8aa3b, v133
	v_mul_f32_e32 v194, 0xbfb8aa3b, v134
	v_mul_f32_e32 v195, 0xbfb8aa3b, v135
	v_mul_f32_e32 v198, 0xbfb8aa3b, v136
	v_mul_f32_e32 v199, 0xbfb8aa3b, v137
	v_mul_f32_e32 v200, 0xbfb8aa3b, v164
	v_mul_f32_e32 v201, 0xbfb8aa3b, v165
	v_mul_f32_e32 v202, 0xbfb8aa3b, v166
	v_mul_f32_e32 v203, 0xbfb8aa3b, v167
	v_mul_f32_e32 v204, 0xbfb8aa3b, v168
	v_mul_f32_e32 v205, 0xbfb8aa3b, v169
	v_mul_f32_e32 v206, 0xbfb8aa3b, v170
	v_mul_f32_e32 v207, 0xbfb8aa3b, v171
	v_exp_f32_e32 v172, v172
	v_exp_f32_e32 v173, v173
	v_exp_f32_e32 v174, v174
	v_exp_f32_e32 v175, v175
	v_exp_f32_e32 v176, v176
	v_exp_f32_e32 v177, v177
	v_exp_f32_e32 v178, v178
	v_exp_f32_e32 v179, v179
	v_exp_f32_e32 v180, v180
	v_exp_f32_e32 v181, v181
	v_exp_f32_e32 v182, v182
	v_exp_f32_e32 v183, v183
	v_exp_f32_e32 v184, v184
	v_exp_f32_e32 v185, v185
	v_exp_f32_e32 v186, v186
	v_exp_f32_e32 v187, v187
	v_exp_f32_e32 v188, v188
	v_exp_f32_e32 v189, v189
	v_exp_f32_e32 v190, v190
	v_exp_f32_e32 v191, v191
	v_exp_f32_e32 v192, v192
	v_exp_f32_e32 v193, v193
	v_exp_f32_e32 v194, v194
	v_exp_f32_e32 v195, v195
	v_exp_f32_e32 v198, v198
	v_exp_f32_e32 v199, v199
	v_exp_f32_e32 v200, v200
	v_exp_f32_e32 v201, v201
	v_exp_f32_e32 v202, v202
	v_exp_f32_e32 v203, v203
	v_exp_f32_e32 v204, v204
	v_exp_f32_e32 v205, v205
	v_exp_f32_e32 v206, v206
	v_exp_f32_e32 v207, v207
	v_add_f32_e32 v172, 1.0, v172
	v_add_f32_e32 v173, 1.0, v173
	v_add_f32_e32 v174, 1.0, v174
	v_add_f32_e32 v175, 1.0, v175
	v_add_f32_e32 v176, 1.0, v176
	v_add_f32_e32 v177, 1.0, v177
	v_add_f32_e32 v178, 1.0, v178
	v_add_f32_e32 v179, 1.0, v179
	v_add_f32_e32 v180, 1.0, v180
	v_add_f32_e32 v181, 1.0, v181
	v_add_f32_e32 v182, 1.0, v182
	v_add_f32_e32 v183, 1.0, v183
	v_add_f32_e32 v184, 1.0, v184
	v_add_f32_e32 v185, 1.0, v185
	v_add_f32_e32 v186, 1.0, v186
	v_add_f32_e32 v187, 1.0, v187
	v_add_f32_e32 v188, 1.0, v188
	v_add_f32_e32 v189, 1.0, v189
	v_add_f32_e32 v190, 1.0, v190
	v_add_f32_e32 v191, 1.0, v191
	v_add_f32_e32 v192, 1.0, v192
	v_add_f32_e32 v193, 1.0, v193
	v_add_f32_e32 v194, 1.0, v194
	v_add_f32_e32 v195, 1.0, v195
	v_add_f32_e32 v198, 1.0, v198
	v_add_f32_e32 v199, 1.0, v199
	v_add_f32_e32 v200, 1.0, v200
	v_add_f32_e32 v201, 1.0, v201
	v_add_f32_e32 v202, 1.0, v202
	v_add_f32_e32 v203, 1.0, v203
	v_add_f32_e32 v204, 1.0, v204
	v_add_f32_e32 v205, 1.0, v205
	v_add_f32_e32 v206, 1.0, v206
	v_add_f32_e32 v207, 1.0, v207
	v_rcp_f32_e32 v172, v172
	v_rcp_f32_e32 v173, v173
	v_rcp_f32_e32 v174, v174
	v_rcp_f32_e32 v175, v175
	v_rcp_f32_e32 v176, v176
	v_rcp_f32_e32 v177, v177
	v_rcp_f32_e32 v178, v178
	v_rcp_f32_e32 v179, v179
	v_rcp_f32_e32 v180, v180
	v_rcp_f32_e32 v181, v181
	v_rcp_f32_e32 v182, v182
	v_rcp_f32_e32 v183, v183
	v_rcp_f32_e32 v184, v184
	v_rcp_f32_e32 v185, v185
	v_rcp_f32_e32 v186, v186
	v_rcp_f32_e32 v187, v187
	v_rcp_f32_e32 v188, v188
	v_rcp_f32_e32 v189, v189
	v_rcp_f32_e32 v190, v190
	v_rcp_f32_e32 v191, v191
	v_rcp_f32_e32 v192, v192
	v_rcp_f32_e32 v193, v193
	v_rcp_f32_e32 v194, v194
	v_rcp_f32_e32 v195, v195
	v_rcp_f32_e32 v198, v198
	v_rcp_f32_e32 v199, v199
	v_rcp_f32_e32 v200, v200
	v_rcp_f32_e32 v201, v201
	v_rcp_f32_e32 v202, v202
	v_rcp_f32_e32 v203, v203
	v_rcp_f32_e32 v204, v204
	v_rcp_f32_e32 v205, v205
	v_rcp_f32_e32 v206, v206
	v_rcp_f32_e32 v207, v207
	v_mul_f32_e32 v112, v112, v172
	v_mul_f32_e32 v113, v113, v173
	v_mul_f32_e32 v114, v114, v174
	v_mul_f32_e32 v115, v115, v175
	v_mul_f32_e32 v116, v116, v176
	v_mul_f32_e32 v117, v117, v177
	v_mul_f32_e32 v118, v118, v178
	v_mul_f32_e32 v119, v119, v179
	v_mul_f32_e32 v120, v120, v180
	v_mul_f32_e32 v121, v121, v181
	v_mul_f32_e32 v122, v122, v182
	v_mul_f32_e32 v123, v123, v183
	v_mul_f32_e32 v124, v124, v184
	v_mul_f32_e32 v125, v125, v185
	v_mul_f32_e32 v126, v126, v186
	v_mul_f32_e32 v127, v127, v187
	v_mul_f32_e32 v128, v128, v188
	v_mul_f32_e32 v129, v129, v189
	v_mul_f32_e32 v130, v130, v190
	v_mul_f32_e32 v131, v131, v191
	v_mul_f32_e32 v132, v132, v192
	v_mul_f32_e32 v133, v133, v193
	v_mul_f32_e32 v134, v134, v194
	v_mul_f32_e32 v135, v135, v195
	v_mul_f32_e32 v136, v136, v198
	v_mul_f32_e32 v137, v137, v199
	v_mul_f32_e32 v164, v164, v200
	v_mul_f32_e32 v165, v165, v201
	v_mul_f32_e32 v166, v166, v202
	v_mul_f32_e32 v167, v167, v203
	v_mul_f32_e32 v168, v168, v204
	v_mul_f32_e32 v169, v169, v205
	v_mul_f32_e32 v170, v170, v206
	v_mul_f32_e32 v171, v171, v207
	v_add_u32_e32 v110, 0x10000, v87
	ds_write_b32 v87, v112
	ds_write_b32 v87, v113 offset:2048
	ds_write_b32 v87, v114 offset:4096
	ds_write_b32 v87, v115 offset:6144
	ds_write_b32 v87, v116 offset:8192
	ds_write_b32 v87, v117 offset:10240
	ds_write_b32 v87, v118 offset:12288
	ds_write_b32 v87, v119 offset:14336
	ds_write_b32 v87, v120 offset:16384
	ds_write_b32 v87, v121 offset:18432
	ds_write_b32 v87, v122 offset:20480
	ds_write_b32 v87, v123 offset:22528
	ds_write_b32 v87, v124 offset:24576
	ds_write_b32 v87, v125 offset:26624
	ds_write_b32 v87, v126 offset:28672
	ds_write_b32 v87, v127 offset:30720
	ds_write_b32 v87, v128 offset:32768
	ds_write_b32 v87, v129 offset:34816
	ds_write_b32 v87, v130 offset:36864
	ds_write_b32 v87, v131 offset:38912
	ds_write_b32 v87, v132 offset:40960
	ds_write_b32 v87, v133 offset:43008
	ds_write_b32 v87, v134 offset:45056
	ds_write_b32 v87, v135 offset:47104
	ds_write_b32 v87, v136 offset:49152
	ds_write_b32 v87, v137 offset:51200
	ds_write_b32 v87, v164 offset:53248
	ds_write_b32 v87, v165 offset:55296
	ds_write_b32 v87, v166 offset:57344
	ds_write_b32 v87, v167 offset:59392
	ds_write_b32 v87, v168 offset:61440
	ds_write_b32 v87, v169 offset:63488
	ds_write_b32 v110, v170
	ds_write_b32 v110, v171 offset:2048
